# attention layer made XCD-local: queues by batch=bx%8 with no stealing, cumsum remapped to batch-owning XCD, in-proj/cumsum/attention barriers XCD-local, GLU->gate/up barrier without L2 writeback
# baseline (speedup 1.0000x reference)
.LBB0_15:
	s_or_b64 exec, exec, s[4:5]
	s_mov_b64 s[10:11], s[84:85]
	s_barrier
	s_load_dwordx2 s[100:101], s[84:85], 0x110
	v_mbcnt_lo_u32_b32 v10, -1, 0
	v_and_b32_e32 v10, 7, v10
	v_lshlrev_b32_e32 v10, 3, v10
	v_add_u32_e32 v10, 0x8000, v10
	s_waitcnt lgkmcnt(0)
	global_load_dwordx2 v[10:11], v10, s[100:101] sc1
	s_waitcnt vmcnt(0)
	v_add_u32_e32 v10, v10, v11
	v_cmp_ne_u32_e32 vcc, 17, v10
	s_nop 1
	s_cmp_eq_u64 vcc, 0
	s_cselect_b32 s100, 1, 0
	s_cselect_b32 s101, 1, 8
	s_nop 0
	v_writelane_b32 v255, s100, 40
	v_writelane_b32 v255, s101, 41
	v_mbcnt_lo_u32_b32 v0, -1, 0
	v_mbcnt_hi_u32_b32 v0, -1, v0
	s_getreg_b32 s0, hwreg(HW_REG_HW_ID, 0, 6)
	s_lshl_b32 s0, s0, 2
	s_and_b32 s0, s0, 0xfc
	s_add_i32 s0, s0, 0
	s_add_i32 s0, s0, 0x23400
	v_mov_b32_e32 v1, s0
	ds_read_b32 v1, v1
	s_mov_b32 s1, s71
	v_and_b32_e32 v37, 63, v0
	s_waitcnt lgkmcnt(0)
	v_readfirstlane_b32 s0, v1
	s_nop 1
	v_lshl_add_u32 v1, s0, 6, v0
	s_mov_b32 s0, s72
	v_ashrrev_i32_e32 v1, 6, v1
	s_lshl_b32 s8, s0, 3
	v_lshl_add_u32 v32, s1, 3, v1
	s_mov_b32 s0, 0x9d00
	v_cmp_gt_i32_e32 vcc, s0, v32
	s_and_saveexec_b64 s[12:13], vcc
	s_cbranch_execz .LBB0_74
	s_load_dwordx2 s[0:1], s[10:11], 0x110
	v_lshl_add_u32 v1, v1, 14, 0
	v_and_b32_e32 v2, 7, v0
	v_lshrrev_b32_e32 v34, 3, v37
	v_lshlrev_b32_e32 v36, 2, v2
	s_waitcnt lgkmcnt(0)
	s_add_u32 s14, s0, 0x9d00000
	s_addc_u32 s15, s1, 0
	s_add_u32 s16, s0, 0x9900000
	s_addc_u32 s17, s1, 0
	s_add_u32 s18, s0, 0x8c00000
	s_addc_u32 s19, s1, 0
	s_add_u32 s20, s0, 0x6000000
	v_lshl_add_u32 v33, v2, 4, v1
	v_mul_u32_u24_e32 v3, 0x84, v34
	v_lshlrev_b32_e32 v0, 3, v2
	v_mul_u32_u24_e32 v2, 0x420, v2
	v_lshlrev_b32_e32 v4, 2, v34
	s_addc_u32 s21, s1, 0
	v_mov_b32_e32 v39, 0
	v_add3_u32 v54, v1, v2, v4
	v_or_b32_e32 v1, 32, v34
	s_add_u32 s22, s0, 0x800000
	v_add_u32_e32 v56, v33, v3
	v_or_b32_e32 v51, 8, v34
	v_or_b32_e32 v52, 16, v34
	v_or_b32_e32 v53, 24, v34
	v_mul_u32_u24_e32 v55, 0x84, v1
	s_addc_u32 s23, s1, 0
	v_mov_b32_e32 v35, v39
	s_mov_b64 s[24:25], 0
	s_movk_i32 s9, 0x57ff
	s_mov_b32 s33, 0x83ff
	s_movk_i32 s38, 0xc7f
	s_movk_i32 s39, 0xc80
	s_movk_i32 s40, 0x67f
	s_movk_i32 s41, 0x87f
	s_movk_i32 s42, 0x380
	v_add_u32_e32 v57, 0x420, v56
	v_add_u32_e32 v58, 0x428, v56
	v_add_u32_e32 v59, 0x840, v56
	v_add_u32_e32 v60, 0x848, v56
	v_add_u32_e32 v61, 0xc60, v56
	v_add_u32_e32 v62, 0xc68, v56
	v_add_u32_e32 v63, 0x1080, v56
	v_add_u32_e32 v64, 0x1088, v56
	v_add_u32_e32 v65, 0x14a0, v56
	v_add_u32_e32 v66, 0x14a8, v56
	v_add_u32_e32 v67, 0x18c0, v56
	v_add_u32_e32 v68, 0x18c8, v56
	v_add_u32_e32 v69, 0x1ce0, v56
	v_add_u32_e32 v70, 0x1ce8, v56
	s_movk_i32 s43, 0x4ec5
	s_movk_i32 s44, 0x5f
	s_mov_b32 s45, 0x18000
	s_mov_b32 s46, 0x30000
	s_mov_b32 s47, 0xb00000
	s_mov_b32 s48, 0x580000
	s_mov_b32 s49, 0x8000
	s_mov_b32 s50, 0x10000
	s_mov_b32 s51, 0x20000
	s_mov_b32 s52, 0x28000
	s_mov_b32 s53, 0x38000
	s_mov_b32 s54, 0x2e8ba2e9
	s_movk_i32 s55, 0xff80
	s_mov_b32 s56, 0x16000
	s_mov_b32 s57, 0x2c000
	s_mov_b32 s58, 0x42000
	s_mov_b32 s59, 0x58000
	s_mov_b32 s60, 0x6e000
	s_mov_b32 s61, 0x9cff
	v_mov_b32_e32 v71, 0x100
	v_mov_b32_e32 v72, 0xf8
	v_mov_b32_e32 v73, 0x400000
	v_lshlrev_b32_e32 v40, 2, v36
	v_lshlrev_b32_e32 v42, 1, v0
	v_mov_b32_e32 v74, 0x200000
	v_mov_b32_e32 v75, 0xc08000
	v_mov_b32_e32 v76, 0x2000
	v_mov_b32_e32 v77, 0x680000
	v_mov_b32_e32 v78, 0x48
	v_mov_b32_e32 v79, 5
	v_mov_b32_e32 v80, 4
	v_mov_b32_e32 v81, 6
	v_mov_b32_e32 v82, v32
	s_branch .LBB0_19

.LBB0_559:
	s_andn2_saveexec_b64 s[2:3], s[10:11]
	s_cbranch_execz .LBB0_592
	s_mov_b64 s[10:11], exec
	v_readlane_b32 s2, v255, 40
	s_nop 0
	s_cmp_lg_u32 s2, 0
	s_cbranch_scc1 .Lglu_nowb
	buffer_wbl2 sc1
.Lglu_nowb:
	s_waitcnt lgkmcnt(0)
	s_waitcnt vmcnt(0)
	v_mbcnt_lo_u32_b32 v0, s10, 0
	v_mbcnt_hi_u32_b32 v0, s11, v0
	v_cmp_eq_u32_e32 vcc, 0, v0
	s_and_saveexec_b64 s[12:13], vcc
	s_cbranch_execz .LBB0_562
	s_bcnt1_i32_b64 s2, s[10:11]
	v_mov_b32_e32 v3, s2
	global_atomic_add v3, v254, v3, s[6:7] offset:1024 sc0

.LBB0_726:
	s_andn2_saveexec_b64 s[2:3], s[10:11]
	s_cbranch_execz .LBB0_759
	s_mov_b64 s[10:11], exec
	v_readlane_b32 s2, v255, 40
	s_nop 0
	s_cmp_lg_u32 s2, 0
	s_cbranch_scc1 .LBB0_756
	buffer_wbl2 sc1
	s_waitcnt lgkmcnt(0)
	s_waitcnt vmcnt(0)
	v_mbcnt_lo_u32_b32 v0, s10, 0
	v_mbcnt_hi_u32_b32 v0, s11, v0
	v_cmp_eq_u32_e32 vcc, 0, v0
	s_and_saveexec_b64 s[12:13], vcc
	s_cbranch_execz .LBB0_729
	s_bcnt1_i32_b64 s2, s[10:11]
	v_mov_b32_e32 v3, s2
	global_atomic_add v3, v254, v3, s[6:7] offset:1024 sc0

.LBB0_759:
	s_or_b64 exec, exec, s[4:5]
	s_mov_b64 s[6:7], s[84:85]
	s_mov_b32 s4, s71
	s_waitcnt lgkmcnt(0)
	s_barrier
	s_cmp_gt_i32 s4, 63
	s_cbranch_scc1 .LBB0_765
	s_and_b32 s2, s4, 7
	s_lshl_b32 s2, s2, 3
	s_lshr_b32 s4, s4, 3
	s_or_b32 s4, s4, s2
	v_mbcnt_lo_u32_b32 v0, -1, 0
	v_mbcnt_hi_u32_b32 v0, -1, v0
	s_getreg_b32 s2, hwreg(HW_REG_HW_ID, 0, 6)
	s_lshl_b32 s2, s2, 2
	s_and_b32 s2, s2, 0xfc
	s_add_i32 s2, s2, 0
	s_add_i32 s2, s2, 0x23400
	v_mov_b32_e32 v2, s2
	ds_read_b32 v2, v2
	s_load_dwordx2 s[6:7], s[6:7], 0x110
	s_ashr_i32 s2, s4, 3
	s_and_b32 s5, s4, 7
	s_waitcnt lgkmcnt(0)
	v_readfirstlane_b32 s3, v2
	s_nop 1
	v_lshl_add_u32 v12, s3, 6, v0
	s_ashr_i32 s3, s2, 31
	v_lshlrev_b32_e32 v2, 3, v12
	s_lshl_b64 s[2:3], s[2:3], 17
	v_ashrrev_i32_e32 v3, 31, v2
	s_add_u32 s2, s6, s2
	s_addc_u32 s3, s7, s3
	v_lshlrev_b64 v[4:5], 5, v[2:3]
	v_lshl_add_u64 v[4:5], s[2:3], 0, v[4:5]
	s_lshl_b32 s50, s5, 2
	v_lshl_add_u64 v[4:5], v[4:5], 0, s[50:51]
	s_mov_b64 s[2:3], 0x500000
	v_lshl_add_u64 v[6:7], v[4:5], 0, s[2:3]
	s_mov_b32 s2, 0x500000
	v_add_co_u32_e32 v4, vcc, s2, v4
	v_mov_b32_e32 v0, 0
	s_nop 0
	v_addc_co_u32_e32 v5, vcc, 0, v5, vcc
	global_load_dword v4, v[4:5], off
	s_nop 0
	global_load_dword v5, v[6:7], off offset:32
	global_load_dword v8, v[6:7], off offset:64
	global_load_dword v9, v[6:7], off offset:96
	global_load_dword v13, v[6:7], off offset:128
	global_load_dword v14, v[6:7], off offset:160
	global_load_dword v15, v[6:7], off offset:192
	global_load_dword v16, v[6:7], off offset:224
	v_lshl_add_u32 v17, v12, 2, 0
	v_cmp_lt_i32_e32 vcc, 0, v12
	s_waitcnt vmcnt(7)
	v_add_f32_e32 v10, 0, v4
	s_waitcnt vmcnt(6)
	v_add_f32_e32 v11, v10, v5
	s_waitcnt vmcnt(5)
	v_add_f32_e32 v8, v11, v8
	s_waitcnt vmcnt(4)
	v_add_f32_e32 v9, v8, v9
	s_waitcnt vmcnt(3)
	v_add_f32_e32 v6, v9, v13
	s_waitcnt vmcnt(2)
	v_add_f32_e32 v7, v6, v14
	s_waitcnt vmcnt(1)
	v_add_f32_e32 v4, v7, v15
	s_waitcnt vmcnt(0)
	v_add_f32_e32 v5, v4, v16
	v_mov_b32_e32 v13, 0
	ds_write_b32 v17, v13
	ds_write_b32 v17, v13 offset:4096
	ds_write_b32 v17, v5 offset:2048
	v_mov_b32_e32 v0, v5
	s_waitcnt lgkmcnt(0)
	s_barrier
	ds_read_b32 v13, v17 offset:2044
	s_waitcnt lgkmcnt(0)
	v_add_f32_e32 v0, v0, v13
	ds_write_b32 v17, v0 offset:6144
	s_waitcnt lgkmcnt(0)
	s_barrier
	ds_read_b32 v13, v17 offset:6136
	s_waitcnt lgkmcnt(0)
	v_add_f32_e32 v0, v0, v13
	ds_write_b32 v17, v0 offset:2048
	s_waitcnt lgkmcnt(0)
	s_barrier
	ds_read_b32 v13, v17 offset:2032
	s_waitcnt lgkmcnt(0)
	v_add_f32_e32 v0, v0, v13
	ds_write_b32 v17, v0 offset:6144
	s_waitcnt lgkmcnt(0)
	s_barrier
	ds_read_b32 v13, v17 offset:6112
	s_waitcnt lgkmcnt(0)
	v_add_f32_e32 v0, v0, v13
	ds_write_b32 v17, v0 offset:2048
	s_waitcnt lgkmcnt(0)
	s_barrier
	ds_read_b32 v13, v17 offset:1984
	s_waitcnt lgkmcnt(0)
	v_add_f32_e32 v0, v0, v13
	ds_write_b32 v17, v0 offset:6144
	s_waitcnt lgkmcnt(0)
	s_barrier
	ds_read_b32 v13, v17 offset:6016
	s_waitcnt lgkmcnt(0)
	v_add_f32_e32 v0, v0, v13
	ds_write_b32 v17, v0 offset:2048
	s_waitcnt lgkmcnt(0)
	s_barrier
	ds_read_b32 v13, v17 offset:1792
	s_waitcnt lgkmcnt(0)
	v_add_f32_e32 v0, v0, v13
	ds_write_b32 v17, v0 offset:6144
	s_waitcnt lgkmcnt(0)
	s_barrier
	ds_read_b32 v13, v17 offset:5632
	s_waitcnt lgkmcnt(0)
	v_add_f32_e32 v0, v0, v13
	ds_write_b32 v17, v0 offset:2048
	s_waitcnt lgkmcnt(0)
	s_barrier
	ds_read_b32 v13, v17 offset:1024
	s_waitcnt lgkmcnt(0)
	v_add_f32_e32 v0, v0, v13
	ds_write_b32 v17, v0 offset:6144
	s_waitcnt lgkmcnt(0)
	s_barrier
	ds_read_b32 v0, v17 offset:6140
	s_waitcnt lgkmcnt(0)

.LBB0_837:
	s_and_saveexec_b64 s[6:7], s[4:5]
	s_cbranch_execz .Lq_pub_done
	s_cmp_eq_u32 s101, 0
	s_cbranch_scc1 .Lq_try
	s_waitcnt vmcnt(32)
	v_readfirstlane_b32 s3, v222
	s_and_b32 s2, s101, 0xff
	s_mov_b32 s101, 0
	s_cmp_lt_u32 s3, 0x100
	s_cbranch_scc1 .Lq_got
	s_add_i32 s100, s100, 1
	v_readlane_b32 s2, v255, 41
	s_nop 0
	s_cmp_lt_u32 s100, s2
	s_cbranch_scc1 .Lq_try
	s_branch .Lq_none
.Lq_try:
	v_readlane_b32 s2, v255, 10
	s_nop 0
	s_add_i32 s2, s2, s100
	s_and_b32 s2, s2, 7
	s_lshl_b32 s3, s2, 9
	s_add_i32 s3, s3, 0x300
	v_mov_b32_e32 v3, s3
	v_mov_b32_e32 v2, 1
	global_atomic_add v2, v3, v2, s[82:83] offset:256 sc0
	s_waitcnt vmcnt(0)
	v_readfirstlane_b32 s3, v2
	s_nop 0
	s_cmp_lt_u32 s3, 0x100
	s_cbranch_scc1 .Lq_got
	s_add_i32 s100, s100, 1
	v_readlane_b32 s2, v255, 41
	s_nop 0
	s_cmp_lt_u32 s100, s2
	s_cbranch_scc1 .Lq_try

.Lq_got:
	s_lshl_b32 s2, s2, 8
	s_or_b32 s2, s2, s3
	v_mov_b32_e32 v0, s2
	v_mov_b32_e32 v2, s49
	ds_write_b32 v2, v0
	s_cmp_lt_u32 s3, 0x100
	s_cbranch_scc0 .Lq_pub_done
	v_readlane_b32 s2, v255, 10
	s_nop 0
	s_add_i32 s2, s2, s100
	s_and_b32 s2, s2, 7
	s_or_b32 s101, s2, 0x100
	s_lshl_b32 s3, s2, 9
	s_add_i32 s3, s3, 0x300
	v_mov_b32_e32 v3, s3
	v_mov_b32_e32 v222, 1
	global_atomic_add v222, v3, v222, s[82:83] offset:256 sc0
.Lq_pub_done:
	s_or_b64 exec, exec, s[6:7]
	v_mov_b32_e32 v0, s49
	s_waitcnt lgkmcnt(0)
	s_barrier
	ds_read_b32 v0, v0
	s_waitcnt lgkmcnt(0)
	s_barrier
	v_readfirstlane_b32 s2, v0
	s_nop 0
	s_cmpk_gt_i32 s2, 0x7ff
	s_cbranch_scc1 .LBB0_886
	s_lshr_b32 s3, s2, 8
	s_and_b32 s2, s2, 0xff
	s_cmp_lt_u32 s2, 64
	s_cbranch_scc0 .Lq_mixed
	s_lshr_b32 s6, s2, 2
	s_sub_i32 s45, 32, s6
	s_and_b32 s6, s2, 3
	s_lshl_b32 s3, s3, 2
	s_add_i32 s78, s3, s6
	s_branch .LBB0_845
.Lq_mixed:
	s_sub_i32 s2, s2, 64
	s_mul_i32 s6, s2, 0xaaab
	s_lshr_b32 s6, s6, 19
	s_sub_i32 s45, 16, s6
	s_mul_i32 s6, s6, 12
	s_sub_i32 s2, s2, s6
	s_cmp_lt_u32 s2, 4
	s_cbranch_scc0 .Lq_fox
	s_lshl_b32 s6, s3, 2
	s_add_i32 s78, s6, s2
	s_branch .LBB0_845
.Lq_fox:
	s_sub_i32 s2, s2, 4
	s_lshl_b32 s6, s3, 3
	s_add_i32 s78, s6, s2
	s_branch .LBB0_872
